# MLA attention: one static priority raise for waves 0-3 (mirror of the previous trial)
# baseline (speedup 1.0000x reference)
; template <int VAR>
; __device__ __forceinline__ void attn_unit(LAS unsigned char* lds, const Desc& d, int u) {
;     ...
;     else if (VAR == 1) { const int nqb = T / 256, qb = u % nqb; head = (u / nqb) & 15; seq = u / (nqb * 16); qpos0 = qb * 256 + 32 * wid;
;         t_lo = 0; t_hi = T / 64; wt_lo = t_lo; wt_hi = t_hi; qcol = head * 96; kcol = head * 128; vcol = head * 128 + 64; }
;     else {
;         const int rows = T / 64, nrb = rows / 4, rb = u % nrb; head = (u / nrb) & 15; seq = u / (nrb * 16); grow = 4 * rb + 2 * (wid >> 2); qpos0 = 0;
;         int k0 = grow - 4; k0 = k0 < 0 ? 0 : k0; k0 = k0 > rows - 9 ? rows - 9 : k0; wt_lo = k0; wt_hi = k0 + 9;
;         int a = 4 * rb - 4; a = a < 0 ? 0 : a; a = a > rows - 9 ? rows - 9 : a; int b = 4 * rb - 2; b = b < 0 ? 0 : b; b = b > rows - 9 ? rows - 9 : b; t_lo = a; t_hi = b + 9;
;         kc0 = 16 * (wid & 3) - 8; kc0 = kc0 < 0 ? 0 : kc0; kc0 = kc0 > 32 ? 32 : kc0;
;         qrow_l = grow + (r32 >> 4); qcol_l = 16 * (wid & 3) + (r32 & 15);
;         rs_l = qrow_l - 4; rs_l = rs_l < 0 ? 0 : rs_l; rs_l = rs_l > rows - 8 ? rows - 8 : rs_l;
;         qcol = head * 64; kcol = 1024 + head * 64; vcol = 2048 + head * 64; }
;     const int qtok_l = VAR == 2 ? qrow_l * 64 + qcol_l : qpos0 + r32;
;     const size_t rowb = (size_t)seq * T;
;     const int skey = tid >> 3, sc = tid & 7, skey2 = tid >> 2, sc2 = tid & 3;
;     const bf16_t* kg = d.K + (rowb + skey) * d.ldk + kcol + sc * 8;
;     const bf16_t* vg = d.V + (rowb + skey) * d.ldv + vcol + sc * 8;
;     const bf16_t* k2g = (VAR == 1) ? d.K2 + (rowb + skey2) * d.ldk2 + 640 + sc2 * 8 : nullptr;
;     const float* ktab = (VAR == 0) ? d.tab + ((size_t)skey * 32 + 8 * (sc & 3)) * 2 : nullptr;
;     const float ksgn = sc < 4 ? -1.f : 1.f;
;     const int klds = skey * KSTR + sc * 16, vlds = ((skey >> 3) * 2 + (sc >> 2)) * 512 + (skey & 7) * 64 + (sc & 3) * 16, k2lds = skey2 * KSTR + 128 + sc2 * 16;
;     u32x4 kreg[2], vreg[1], k2reg[2]; f32x4 kcs[2][4]; k2reg[0] = k2reg[1] = (u32x4){0, 0, 0, 0};
.LBB0_1121:
	s_abs_i32 s7, s1
	v_readlane_b32 s8, v255, 4
	s_mul_hi_u32 s8, s7, s8
	v_readlane_b32 s12, v255, 8
	s_mul_i32 s9, s8, s12
	s_sub_i32 s9, s7, s9
	s_ashr_i32 s6, s1, 31
	s_add_i32 s10, s8, 1
	s_sub_i32 s11, s9, s12
	s_cmp_ge_u32 s9, s12
	s_cselect_b32 s8, s10, s8
	s_cselect_b32 s9, s11, s9
	s_add_i32 s10, s8, 1
	s_cmp_ge_u32 s9, s12
	s_cselect_b32 s8, s10, s8
	v_readlane_b32 s10, v255, 6
	s_mul_hi_u32 s10, s7, s10
	v_readlane_b32 s13, v255, 5
	s_xor_b32 s8, s8, s6
	s_mul_i32 s11, s10, s13
	s_sub_i32 s9, s8, s6
	s_sub_i32 s7, s7, s11
	s_and_b32 s8, s9, 15
	s_add_i32 s11, s10, 1
	s_sub_i32 s12, s7, s13
	s_cmp_ge_u32 s7, s13
	s_cselect_b32 s10, s11, s10
	s_cselect_b32 s7, s12, s7
	s_add_i32 s11, s10, 1
	s_cmp_ge_u32 s7, s13
	s_cselect_b32 s7, s11, s10
	s_xor_b32 s7, s7, s6
	v_mov_b32_e32 v70, v203
	s_sub_i32 s6, s7, s6
	s_ashr_i32 s7, s6, 31
	v_readlane_b32 s10, v255, 3
	v_ashrrev_i32_e32 v50, 3, v70
	s_lshl_b64 s[6:7], s[6:7], s10
	v_ashrrev_i32_e32 v51, 31, v50
	v_lshl_add_u64 v[2:3], s[6:7], 0, v[50:51]
	v_readlane_b32 s10, v253, 33
	v_lshlrev_b64 v[200:201], 12, v[2:3]
	v_readlane_b32 s11, v253, 34
	v_and_b32_e32 v52, 7, v70
	s_lshl_b32 s36, s8, 8
	v_lshl_add_u64 v[2:3], s[10:11], 0, v[200:201]
	v_lshl_add_u64 v[2:3], v[2:3], 0, s[36:37]
	v_lshlrev_b32_e32 v0, 4, v52
	v_lshl_add_u64 v[78:79], v[2:3], 0, v[0:1]
	global_load_dwordx4 v[30:33], v[78:79], off
	v_ashrrev_i32_e32 v6, 2, v70
	v_ashrrev_i32_e32 v7, 31, v6
	v_lshl_add_u64 v[214:215], s[6:7], 0, v[6:7]
	v_mov_b64_e32 v[2:3], s[4:5]
	s_movk_i32 s13, 0x600
	v_and_b32_e32 v4, 3, v70
	v_mad_u64_u32 v[2:3], s[10:11], v214, s13, v[2:3]
	v_mad_i32_i24 v3, v215, s13, v3
	v_lshlrev_b32_e32 v212, 4, v4
	v_mov_b32_e32 v213, v1
	v_lshl_add_u64 v[2:3], v[2:3], 0, v[212:213]
	s_mov_b64 s[10:11], 0x500
	v_lshl_add_u64 v[80:81], v[2:3], 0, s[10:11]
	s_movk_i32 s10, 0x100
	v_readfirstlane_b32 s12, v70
	v_cmp_gt_i32_e64 s[40:41], s10, v70
	s_cmp_ge_u32 s12, 0x100
	s_cbranch_scc1 .Lmla_prio_done
	s_setprio 1
